# QK-norm: the 16 rope-table loads of an iteration's four chunks issued together after the rows are known (own registers, full exec) instead of inside each chunk's masked block
# baseline (speedup 1.0000x reference)
; #define GAS __attribute__((address_space(1)))
; DI float bflo(unsigned u) { return __uint_as_float(u << 16); }
; DI void phase_qknorm(const Ctx& C, bf16_t* Z, const float* qkg  , const float* ropec, const float* ropes) {
;     ...
;         for (int j = 0; j < 4; ++j) {
;             const int it = it0 + j * NG; const int itc = min(it, NIT - 1); const int row = itc / 42, s = itc % 42;
;             const int gi = s < 8 ? 0 : s < 10 ? 1 : s < 18 ? 2 : s < 26 ? 3 : s < 34 ? 4 : 5;
;             const bool rope = (gi != 2 && gi != 3), isq = !(gi & 1);
;             const u32x4 rw = raw[j];
;             float x[8] = {bflo(rw.x), bfhi(rw.x), bflo(rw.y), bfhi(rw.y), bflo(rw.z), bfhi(rw.z), bflo(rw.w), bfhi(rw.w)};
;             float ss = 0.f;
; #pragma unroll
;             for (int i = 0; i < 8; ++i) ss += x[i] * x[i];
;             ss += shx(ss, 1, lane); ss += shx(ss, 2, lane); ss += shx(ss, 4, lane);
;             const float rstd = 1.f / sqrtf(ss * (1.f / 64.f) + EPS);
;             const f32x4 g0 = *(const GAS f32x4*)(qkg + gi * 64 + 8 * t8), g1 = *(const GAS f32x4*)(qkg + gi * 64 + 8 * t8 + 4);
;             x[0] *= rstd * g0.x; x[1] *= rstd * g0.y; x[2] *= rstd * g0.z; x[3] *= rstd * g0.w; x[4] *= rstd * g1.x; x[5] *= rstd * g1.y; x[6] *= rstd * g1.z; x[7] *= rstd * g1.w;
;             float px[8];
; #pragma unroll
;             for (int i = 0; i < 8; ++i) px[i] = shx(x[i], 2, lane);
;             if (rope && row < NLAT) {
;                 const int tok = row & (SEQ - 1), ab = tok * 32 + (t8 & 1) * 8 + (t8 >> 2) * 16;
;                 const f32x4 c0 = *(const GAS f32x4*)(ropec + ab), c1 = *(const GAS f32x4*)(ropec + ab + 4), s0 = *(const GAS f32x4*)(ropes + ab), s1 = *(const GAS f32x4*)(ropes + ab + 4);
;                 const float cc[8] = {c0.x, c0.y, c0.z, c0.w, c1.x, c1.y, c1.z, c1.w}, sn[8] = {s0.x, s0.y, s0.z, s0.w, s1.x, s1.y, s1.z, s1.w};
;                 const float sg = (t8 & 2) ? 1.f : -1.f;
; #pragma unroll
;                 for (int i = 0; i < 8; ++i) x[i] = x[i] * cc[i] + sg * px[i] * sn[i];
;             }
;             if (isq) {
; #pragma unroll
;                 for (int i = 0; i < 8; ++i) x[i] *= QSCALE;
;             }
;             u32x4 w; w.x = pk2(x[0], x[1]); w.y = pk2(x[2], x[3]); w.z = pk2(x[4], x[5]); w.w = pk2(x[6], x[7]);
;             if (it < NIT) *(GAS u32x4*)pp[j] = w;
.LBB0_621:
	s_or_b64 exec, exec, s[10:11]
	s_mov_b32 s68, 0xffe0
	v_lshlrev_b32_e32 v70, 5, v44
	v_lshlrev_b32_e32 v71, 5, v41
	v_lshlrev_b32_e32 v72, 5, v39
	v_lshlrev_b32_e32 v73, 5, v36
	v_and_or_b32 v70, v70, s68, v35
	v_and_or_b32 v71, v71, s68, v35
	v_and_or_b32 v72, v72, s68, v35
	v_and_or_b32 v73, v73, s68, v35
	v_lshlrev_b32_e32 v70, 2, v70
	v_lshlrev_b32_e32 v71, 2, v71
	v_lshlrev_b32_e32 v72, 2, v72
	v_lshlrev_b32_e32 v73, 2, v73
	global_load_dwordx4 v[158:161], v70, s[14:15] offset:16
	global_load_dwordx4 v[162:165], v70, s[14:15]
	global_load_dwordx4 v[166:169], v70, s[16:17] offset:16
	global_load_dwordx4 v[170:173], v70, s[16:17]
	global_load_dwordx4 v[174:177], v71, s[14:15] offset:16
	global_load_dwordx4 v[178:181], v71, s[14:15]
	global_load_dwordx4 v[182:185], v71, s[16:17] offset:16
	global_load_dwordx4 v[186:189], v71, s[16:17]
	global_load_dwordx4 v[190:193], v72, s[14:15] offset:16
	global_load_dwordx4 v[210:213], v72, s[14:15]
	global_load_dwordx4 v[214:217], v72, s[16:17] offset:16
	global_load_dwordx4 v[218:221], v72, s[16:17]
	global_load_dwordx4 v[222:225], v73, s[14:15] offset:16
	global_load_dwordx4 v[240:243], v73, s[14:15]
	global_load_dwordx4 v[244:247], v73, s[16:17] offset:16
	global_load_dwordx4 v[138:141], v73, s[16:17]
	v_lshlrev_b32_e32 v28, 8, v45
	v_mov_b32_e32 v29, v1
	v_lshl_add_u64 v[46:47], v[18:19], 0, v[28:29]
	global_load_dwordx4 v[28:31], v[46:47], off
	s_nop 0
	global_load_dwordx4 v[46:49], v[46:47], off offset:16
	s_waitcnt vmcnt(5)
	v_lshlrev_b32_e32 v52, 16, v14
	v_and_b32_e32 v53, 0xffff0000, v14
	v_and_b32_e32 v50, 0xffff0000, v17
	v_lshlrev_b32_e32 v51, 16, v17
	v_lshlrev_b32_e32 v54, 16, v15
	v_and_b32_e32 v55, 0xffff0000, v15
	v_lshlrev_b32_e32 v56, 16, v16
	v_and_b32_e32 v57, 0xffff0000, v16
	v_pk_mul_f32 v[16:17], v[52:53], v[52:53]
	v_pk_mul_f32 v[58:59], v[54:55], v[54:55]
	v_add_f32_e32 v16, v16, v17
	v_add_f32_e32 v16, v58, v16
	v_pk_mul_f32 v[60:61], v[56:57], v[56:57]
	v_add_f32_e32 v16, v59, v16
	v_add_f32_e32 v16, v60, v16
	v_pk_mul_f32 v[14:15], v[50:51], v[50:51]
	v_add_f32_e32 v16, v61, v16
	v_add_f32_e32 v15, v15, v16
	v_add_f32_e32 v14, v14, v15
	ds_bpermute_b32 v15, v32, v14
	s_waitcnt lgkmcnt(0)
	v_add_f32_e32 v14, v14, v15
	ds_bpermute_b32 v15, v33, v14
	s_waitcnt lgkmcnt(0)
	v_add_f32_e32 v14, v14, v15
	ds_bpermute_b32 v15, v34, v14
	s_waitcnt lgkmcnt(0)
	v_add_f32_e32 v14, v14, v15
	v_fmamk_f32 v14, v14, 0x3c800000, v227
	v_mul_f32_e32 v15, 0x4f800000, v14
	v_cmp_gt_f32_e32 vcc, s67, v14
	s_nop 1
	v_cndmask_b32_e32 v14, v14, v15, vcc
	v_sqrt_f32_e32 v15, v14
	s_nop 0
	v_add_u32_e32 v16, -1, v15
	v_add_u32_e32 v17, 1, v15
	v_fma_f32 v58, -v16, v15, v14
	v_fma_f32 v59, -v17, v15, v14
	v_cmp_ge_f32_e64 s[10:11], 0, v58
	s_nop 1
	v_cndmask_b32_e64 v15, v15, v16, s[10:11]
	v_cmp_lt_f32_e64 s[10:11], 0, v59
	s_nop 1
	v_cndmask_b32_e64 v15, v15, v17, s[10:11]
	v_mul_f32_e32 v16, 0x37800000, v15
	v_cndmask_b32_e32 v15, v15, v16, vcc
	v_cmp_class_f32_e32 vcc, v14, v228
	s_nop 1
	v_cndmask_b32_e32 v14, v15, v14, vcc
	v_div_scale_f32 v15, s[10:11], v14, v14, 1.0
	v_rcp_f32_e32 v16, v15
	v_div_scale_f32 v17, vcc, 1.0, v14, 1.0
	v_cmp_gt_i32_e64 s[10:11], s59, v43
	v_fma_f32 v58, -v15, v16, 1.0
	v_fmac_f32_e32 v16, v58, v16
	v_mul_f32_e32 v58, v17, v16
	v_fma_f32 v59, -v15, v58, v17
	v_fmac_f32_e32 v58, v59, v16
	v_fma_f32 v15, -v15, v58, v17
	v_div_fmas_f32 v15, v15, v16, v58
	v_div_fixup_f32 v14, v15, v14, 1.0
	s_waitcnt vmcnt(1)
	v_pk_mul_f32 v[16:17], v[28:29], v[14:15] op_sel_hi:[1,0]
	v_pk_mul_f32 v[28:29], v[30:31], v[14:15] op_sel_hi:[1,0]
	s_waitcnt vmcnt(0)
	v_pk_mul_f32 v[30:31], v[46:47], v[14:15] op_sel_hi:[1,0]
	v_pk_mul_f32 v[46:47], v[48:49], v[14:15] op_sel_hi:[1,0]
	v_pk_mul_f32 v[14:15], v[16:17], v[52:53]
	v_pk_mul_f32 v[16:17], v[28:29], v[54:55]
	v_pk_mul_f32 v[28:29], v[30:31], v[56:57]
	v_pk_mul_f32 v[30:31], v[46:47], v[50:51] op_sel:[0,1] op_sel_hi:[1,0]
	ds_bpermute_b32 v52, v33, v14
	ds_bpermute_b32 v53, v33, v15
	ds_bpermute_b32 v50, v33, v16
	ds_bpermute_b32 v51, v33, v17
	ds_bpermute_b32 v48, v33, v28
	ds_bpermute_b32 v49, v33, v29
	ds_bpermute_b32 v47, v33, v30
	ds_bpermute_b32 v46, v33, v31
	v_add_u32_e32 v54, -4, v45
	v_cmp_gt_u32_e32 vcc, -2, v54
	s_and_b64 s[20:21], s[10:11], vcc
	s_and_saveexec_b64 s[10:11], s[20:21]
	s_cbranch_execz .LBB0_623
	v_lshlrev_b32_e32 v43, 5, v44
	s_mov_b32 s20, 0xffe0
	v_and_or_b32 v43, v43, s20, v35
	v_lshlrev_b32_e32 v43, 2, v43
	s_waitcnt lgkmcnt(1)
	v_cndmask_b32_e64 v43, v47, -v47, s[0:1]
	s_waitcnt lgkmcnt(0)
	v_cndmask_b32_e64 v47, v46, -v46, s[0:1]
	v_mov_b32_e32 v46, v31
	v_cndmask_b32_e64 v52, v52, -v52, s[0:1]
	v_cndmask_b32_e64 v53, v53, -v53, s[0:1]
	v_cndmask_b32_e64 v50, v50, -v50, s[0:1]
	v_cndmask_b32_e64 v51, v51, -v51, s[0:1]
	v_cndmask_b32_e64 v48, v48, -v48, s[0:1]
	v_cndmask_b32_e64 v49, v49, -v49, s[0:1]
	s_waitcnt vmcnt(3)
	v_mul_f32_e32 v30, v30, v160
	s_waitcnt vmcnt(1)
	v_mul_f32_e32 v160, v43, v168
	v_mov_b32_e32 v168, v161
	v_pk_mul_f32 v[46:47], v[46:47], v[168:169]
	s_waitcnt vmcnt(0)
	v_pk_mul_f32 v[52:53], v[52:53], v[170:171]
	v_pk_mul_f32 v[50:51], v[50:51], v[172:173]
	v_pk_mul_f32 v[48:49], v[48:49], v[166:167]
	v_mov_b32_e32 v31, v46
	v_mov_b32_e32 v161, v47
	v_pk_fma_f32 v[14:15], v[14:15], v[162:163], v[52:53]
	v_pk_fma_f32 v[16:17], v[16:17], v[164:165], v[50:51]
	v_pk_fma_f32 v[28:29], v[28:29], v[158:159], v[48:49]
	v_pk_add_f32 v[30:31], v[30:31], v[160:161]

; #define GAS __attribute__((address_space(1)))
; DI float bflo(unsigned u) { return __uint_as_float(u << 16); }
; DI void phase_qknorm(const Ctx& C, bf16_t* Z, const float* qkg  , const float* ropec, const float* ropes) {
;     ...
;         for (int j = 0; j < 4; ++j) {
;             const int it = it0 + j * NG; const int itc = min(it, NIT - 1); const int row = itc / 42, s = itc % 42;
;             const int gi = s < 8 ? 0 : s < 10 ? 1 : s < 18 ? 2 : s < 26 ? 3 : s < 34 ? 4 : 5;
;             const bool rope = (gi != 2 && gi != 3), isq = !(gi & 1);
;             const u32x4 rw = raw[j];
;             float x[8] = {bflo(rw.x), bfhi(rw.x), bflo(rw.y), bfhi(rw.y), bflo(rw.z), bfhi(rw.z), bflo(rw.w), bfhi(rw.w)};
;             float ss = 0.f;
; #pragma unroll
;             for (int i = 0; i < 8; ++i) ss += x[i] * x[i];
;             ss += shx(ss, 1, lane); ss += shx(ss, 2, lane); ss += shx(ss, 4, lane);
;             const float rstd = 1.f / sqrtf(ss * (1.f / 64.f) + EPS);
;             const f32x4 g0 = *(const GAS f32x4*)(qkg + gi * 64 + 8 * t8), g1 = *(const GAS f32x4*)(qkg + gi * 64 + 8 * t8 + 4);
;             x[0] *= rstd * g0.x; x[1] *= rstd * g0.y; x[2] *= rstd * g0.z; x[3] *= rstd * g0.w; x[4] *= rstd * g1.x; x[5] *= rstd * g1.y; x[6] *= rstd * g1.z; x[7] *= rstd * g1.w;
;             float px[8];
; #pragma unroll
;             for (int i = 0; i < 8; ++i) px[i] = shx(x[i], 2, lane);
;             if (rope && row < NLAT) {
;                 const int tok = row & (SEQ - 1), ab = tok * 32 + (t8 & 1) * 8 + (t8 >> 2) * 16;
;                 const f32x4 c0 = *(const GAS f32x4*)(ropec + ab), c1 = *(const GAS f32x4*)(ropec + ab + 4), s0 = *(const GAS f32x4*)(ropes + ab), s1 = *(const GAS f32x4*)(ropes + ab + 4);
;                 const float cc[8] = {c0.x, c0.y, c0.z, c0.w, c1.x, c1.y, c1.z, c1.w}, sn[8] = {s0.x, s0.y, s0.z, s0.w, s1.x, s1.y, s1.z, s1.w};
;                 const float sg = (t8 & 2) ? 1.f : -1.f;
; #pragma unroll
;                 for (int i = 0; i < 8; ++i) x[i] = x[i] * cc[i] + sg * px[i] * sn[i];
;             }
;             if (isq) {
; #pragma unroll
;                 for (int i = 0; i < 8; ++i) x[i] *= QSCALE;
;             }
;             u32x4 w; w.x = pk2(x[0], x[1]); w.y = pk2(x[2], x[3]); w.z = pk2(x[4], x[5]); w.w = pk2(x[6], x[7]);
;             if (it < NIT) *(GAS u32x4*)pp[j] = w;
.LBB0_627:
	s_or_b64 exec, exec, s[10:11]
	v_lshlrev_b32_e32 v14, 8, v43
	v_mov_b32_e32 v15, v1
	v_lshl_add_u64 v[26:27], v[18:19], 0, v[14:15]
	global_load_dwordx4 v[14:17], v[26:27], off
	s_nop 0
	global_load_dwordx4 v[26:29], v[26:27], off offset:16
	v_lshlrev_b32_e32 v44, 16, v10
	v_and_b32_e32 v45, 0xffff0000, v10
	v_and_b32_e32 v30, 0xffff0000, v13
	v_lshlrev_b32_e32 v31, 16, v13
	v_lshlrev_b32_e32 v46, 16, v11
	v_and_b32_e32 v47, 0xffff0000, v11
	v_lshlrev_b32_e32 v48, 16, v12
	v_and_b32_e32 v49, 0xffff0000, v12
	v_pk_mul_f32 v[12:13], v[44:45], v[44:45]
	v_pk_mul_f32 v[50:51], v[46:47], v[46:47]
	v_add_f32_e32 v12, v12, v13
	v_add_f32_e32 v12, v50, v12
	v_pk_mul_f32 v[52:53], v[48:49], v[48:49]
	v_add_f32_e32 v12, v51, v12
	v_add_f32_e32 v12, v52, v12
	v_pk_mul_f32 v[10:11], v[30:31], v[30:31]
	v_add_f32_e32 v12, v53, v12
	v_add_f32_e32 v11, v11, v12
	v_add_f32_e32 v10, v10, v11
	ds_bpermute_b32 v11, v32, v10
	s_waitcnt lgkmcnt(0)
	v_add_f32_e32 v10, v10, v11
	ds_bpermute_b32 v11, v33, v10
	s_waitcnt lgkmcnt(0)
	v_add_f32_e32 v10, v10, v11
	ds_bpermute_b32 v11, v34, v10
	s_waitcnt lgkmcnt(0)
	v_add_f32_e32 v10, v10, v11
	v_fmamk_f32 v10, v10, 0x3c800000, v227
	v_mul_f32_e32 v11, 0x4f800000, v10
	v_cmp_gt_f32_e32 vcc, s67, v10
	s_nop 1
	v_cndmask_b32_e32 v10, v10, v11, vcc
	v_sqrt_f32_e32 v11, v10
	s_nop 0
	v_add_u32_e32 v12, -1, v11
	v_add_u32_e32 v13, 1, v11
	v_fma_f32 v42, -v12, v11, v10
	v_fma_f32 v50, -v13, v11, v10
	v_cmp_ge_f32_e64 s[6:7], 0, v42
	s_nop 1
	v_cndmask_b32_e64 v11, v11, v12, s[6:7]
	v_cmp_lt_f32_e64 s[6:7], 0, v50
	s_nop 1
	v_cndmask_b32_e64 v11, v11, v13, s[6:7]
	v_mul_f32_e32 v12, 0x37800000, v11
	v_cndmask_b32_e32 v11, v11, v12, vcc
	v_cmp_class_f32_e32 vcc, v10, v228
	s_nop 1
	v_cndmask_b32_e32 v10, v11, v10, vcc
	v_div_scale_f32 v11, s[6:7], v10, v10, 1.0
	v_rcp_f32_e32 v12, v11
	v_div_scale_f32 v13, vcc, 1.0, v10, 1.0
	v_cmp_gt_i32_e64 s[6:7], s59, v37
	v_fma_f32 v42, -v11, v12, 1.0
	v_fmac_f32_e32 v12, v42, v12
	v_mul_f32_e32 v42, v13, v12
	v_fma_f32 v50, -v11, v42, v13
	v_fmac_f32_e32 v42, v50, v12
	v_fma_f32 v11, -v11, v42, v13
	v_div_fmas_f32 v11, v11, v12, v42
	v_div_fixup_f32 v10, v11, v10, 1.0
	s_waitcnt vmcnt(1)
	v_pk_mul_f32 v[12:13], v[14:15], v[10:11] op_sel_hi:[1,0]
	v_pk_mul_f32 v[14:15], v[16:17], v[10:11] op_sel_hi:[1,0]
	s_waitcnt vmcnt(0)
	v_pk_mul_f32 v[16:17], v[26:27], v[10:11] op_sel_hi:[1,0]
	v_pk_mul_f32 v[26:27], v[28:29], v[10:11] op_sel_hi:[1,0]
	v_pk_mul_f32 v[10:11], v[12:13], v[44:45]
	v_pk_mul_f32 v[12:13], v[14:15], v[46:47]
	v_pk_mul_f32 v[14:15], v[16:17], v[48:49]
	v_pk_mul_f32 v[16:17], v[26:27], v[30:31] op_sel:[0,1] op_sel_hi:[1,0]
	ds_bpermute_b32 v42, v33, v10
	ds_bpermute_b32 v44, v33, v11
	ds_bpermute_b32 v30, v33, v12
	ds_bpermute_b32 v31, v33, v13
	ds_bpermute_b32 v28, v33, v14
	ds_bpermute_b32 v29, v33, v15
	ds_bpermute_b32 v27, v33, v16
	ds_bpermute_b32 v26, v33, v17
	v_add_u32_e32 v45, -4, v43
	v_cmp_gt_u32_e32 vcc, -2, v45
	s_and_b64 s[10:11], s[6:7], vcc
	s_and_saveexec_b64 s[6:7], s[10:11]
	s_cbranch_execz .LBB0_630
	v_lshlrev_b32_e32 v41, 5, v41
	s_mov_b32 s10, 0xffe0
	v_and_or_b32 v41, v41, s10, v35
	v_lshlrev_b32_e32 v41, 2, v41
	s_waitcnt lgkmcnt(1)
	v_cndmask_b32_e64 v27, v27, -v27, s[0:1]
	v_cndmask_b32_e64 v62, v42, -v42, s[0:1]
	v_cndmask_b32_e64 v63, v44, -v44, s[0:1]
	v_cndmask_b32_e64 v30, v30, -v30, s[0:1]
	v_cndmask_b32_e64 v31, v31, -v31, s[0:1]
	v_cndmask_b32_e64 v28, v28, -v28, s[0:1]
	v_cndmask_b32_e64 v29, v29, -v29, s[0:1]
	s_waitcnt vmcnt(3)
	v_mul_f32_e32 v16, v16, v176
	s_waitcnt vmcnt(1)
	v_mul_f32_e32 v176, v27, v184
	s_waitcnt lgkmcnt(0)
	v_cndmask_b32_e64 v27, v26, -v26, s[0:1]
	v_mov_b32_e32 v26, v17
	v_mov_b32_e32 v184, v177
	v_pk_mul_f32 v[26:27], v[26:27], v[184:185]
	s_waitcnt vmcnt(0)
	v_pk_mul_f32 v[44:45], v[62:63], v[186:187]
	v_pk_mul_f32 v[30:31], v[30:31], v[188:189]
	v_pk_mul_f32 v[28:29], v[28:29], v[182:183]
	v_mov_b32_e32 v17, v26
	v_mov_b32_e32 v177, v27
	v_pk_fma_f32 v[10:11], v[10:11], v[178:179], v[44:45]
	v_pk_fma_f32 v[12:13], v[12:13], v[180:181], v[30:31]
	v_pk_fma_f32 v[14:15], v[14:15], v[174:175], v[28:29]
	v_pk_add_f32 v[16:17], v[16:17], v[176:177]
	s_or_b64 exec, exec, s[6:7]
	v_cmp_gt_i32_e32 vcc, s90, v37
	s_and_saveexec_b64 s[6:7], vcc
	s_cbranch_execnz .LBB0_631

; #define GAS __attribute__((address_space(1)))
; DI float bflo(unsigned u) { return __uint_as_float(u << 16); }
; DI void phase_qknorm(const Ctx& C, bf16_t* Z, const float* qkg  , const float* ropec, const float* ropes) {
;     ...
;         for (int j = 0; j < 4; ++j) {
;             const int it = it0 + j * NG; const int itc = min(it, NIT - 1); const int row = itc / 42, s = itc % 42;
;             const int gi = s < 8 ? 0 : s < 10 ? 1 : s < 18 ? 2 : s < 26 ? 3 : s < 34 ? 4 : 5;
;             const bool rope = (gi != 2 && gi != 3), isq = !(gi & 1);
;             const u32x4 rw = raw[j];
;             float x[8] = {bflo(rw.x), bfhi(rw.x), bflo(rw.y), bfhi(rw.y), bflo(rw.z), bfhi(rw.z), bflo(rw.w), bfhi(rw.w)};
;             float ss = 0.f;
; #pragma unroll
;             for (int i = 0; i < 8; ++i) ss += x[i] * x[i];
;             ss += shx(ss, 1, lane); ss += shx(ss, 2, lane); ss += shx(ss, 4, lane);
;             const float rstd = 1.f / sqrtf(ss * (1.f / 64.f) + EPS);
;             const f32x4 g0 = *(const GAS f32x4*)(qkg + gi * 64 + 8 * t8), g1 = *(const GAS f32x4*)(qkg + gi * 64 + 8 * t8 + 4);
;             x[0] *= rstd * g0.x; x[1] *= rstd * g0.y; x[2] *= rstd * g0.z; x[3] *= rstd * g0.w; x[4] *= rstd * g1.x; x[5] *= rstd * g1.y; x[6] *= rstd * g1.z; x[7] *= rstd * g1.w;
;             float px[8];
; #pragma unroll
;             for (int i = 0; i < 8; ++i) px[i] = shx(x[i], 2, lane);
;             if (rope && row < NLAT) {
;                 const int tok = row & (SEQ - 1), ab = tok * 32 + (t8 & 1) * 8 + (t8 >> 2) * 16;
;                 const f32x4 c0 = *(const GAS f32x4*)(ropec + ab), c1 = *(const GAS f32x4*)(ropec + ab + 4), s0 = *(const GAS f32x4*)(ropes + ab), s1 = *(const GAS f32x4*)(ropes + ab + 4);
;                 const float cc[8] = {c0.x, c0.y, c0.z, c0.w, c1.x, c1.y, c1.z, c1.w}, sn[8] = {s0.x, s0.y, s0.z, s0.w, s1.x, s1.y, s1.z, s1.w};
;                 const float sg = (t8 & 2) ? 1.f : -1.f;
; #pragma unroll
;                 for (int i = 0; i < 8; ++i) x[i] = x[i] * cc[i] + sg * px[i] * sn[i];
;             }
;             if (isq) {
; #pragma unroll
;                 for (int i = 0; i < 8; ++i) x[i] *= QSCALE;
;             }
;             u32x4 w; w.x = pk2(x[0], x[1]); w.y = pk2(x[2], x[3]); w.z = pk2(x[4], x[5]); w.w = pk2(x[6], x[7]);
;             if (it < NIT) *(GAS u32x4*)pp[j] = w;
.LBB0_635:
	s_or_b64 exec, exec, s[6:7]
	v_lshlrev_b32_e32 v10, 8, v15
	v_mov_b32_e32 v11, v1
	v_lshl_add_u64 v[16:17], v[18:19], 0, v[10:11]
	global_load_dwordx4 v[10:13], v[16:17], off
	s_waitcnt lgkmcnt(0)
	global_load_dwordx4 v[24:27], v[16:17], off offset:16
	v_lshlrev_b32_e32 v28, 16, v6
	v_and_b32_e32 v29, 0xffff0000, v6
	v_and_b32_e32 v16, 0xffff0000, v9
	v_lshlrev_b32_e32 v17, 16, v9
	v_lshlrev_b32_e32 v30, 16, v7
	v_and_b32_e32 v31, 0xffff0000, v7
	v_lshlrev_b32_e32 v40, 16, v8
	v_and_b32_e32 v41, 0xffff0000, v8
	v_pk_mul_f32 v[8:9], v[28:29], v[28:29]
	v_pk_mul_f32 v[42:43], v[30:31], v[30:31]
	v_add_f32_e32 v8, v8, v9
	v_add_f32_e32 v8, v42, v8
	v_pk_mul_f32 v[44:45], v[40:41], v[40:41]
	v_add_f32_e32 v8, v43, v8
	v_add_f32_e32 v8, v44, v8
	v_pk_mul_f32 v[6:7], v[16:17], v[16:17]
	v_add_f32_e32 v8, v45, v8
	v_add_f32_e32 v7, v7, v8
	v_add_f32_e32 v6, v6, v7
	ds_bpermute_b32 v7, v32, v6
	s_waitcnt lgkmcnt(0)
	v_add_f32_e32 v6, v6, v7
	ds_bpermute_b32 v7, v33, v6
	s_waitcnt lgkmcnt(0)
	v_add_f32_e32 v6, v6, v7
	ds_bpermute_b32 v7, v34, v6
	s_waitcnt lgkmcnt(0)
	v_add_f32_e32 v6, v6, v7
	v_fmamk_f32 v6, v6, 0x3c800000, v227
	v_mul_f32_e32 v7, 0x4f800000, v6
	v_cmp_gt_f32_e32 vcc, s67, v6
	s_nop 1
	v_cndmask_b32_e32 v6, v6, v7, vcc
	v_sqrt_f32_e32 v7, v6
	s_nop 0
	v_add_u32_e32 v8, -1, v7
	v_add_u32_e32 v9, 1, v7
	v_fma_f32 v14, -v8, v7, v6
	v_fma_f32 v42, -v9, v7, v6
	v_cmp_ge_f32_e64 s[4:5], 0, v14
	v_add_u32_e32 v14, -4, v15
	s_nop 0
	v_cndmask_b32_e64 v7, v7, v8, s[4:5]
	v_cmp_lt_f32_e64 s[4:5], 0, v42
	s_nop 1
	v_cndmask_b32_e64 v7, v7, v9, s[4:5]
	v_mul_f32_e32 v8, 0x37800000, v7
	v_cndmask_b32_e32 v7, v7, v8, vcc
	v_cmp_class_f32_e32 vcc, v6, v228
	s_nop 1
	v_cndmask_b32_e32 v6, v7, v6, vcc
	v_div_scale_f32 v7, s[4:5], v6, v6, 1.0
	v_rcp_f32_e32 v8, v7
	v_div_scale_f32 v9, vcc, 1.0, v6, 1.0
	v_fma_f32 v42, -v7, v8, 1.0
	v_fmac_f32_e32 v8, v42, v8
	v_mul_f32_e32 v42, v9, v8
	v_fma_f32 v43, -v7, v42, v9
	v_fmac_f32_e32 v42, v43, v8
	v_fma_f32 v7, -v7, v42, v9
	v_div_fmas_f32 v7, v7, v8, v42
	v_div_fixup_f32 v6, v7, v6, 1.0
	s_waitcnt vmcnt(1)
	v_pk_mul_f32 v[8:9], v[10:11], v[6:7] op_sel_hi:[1,0]
	v_pk_mul_f32 v[10:11], v[12:13], v[6:7] op_sel_hi:[1,0]
	s_waitcnt vmcnt(0)
	v_pk_mul_f32 v[12:13], v[24:25], v[6:7] op_sel_hi:[1,0]
	v_pk_mul_f32 v[24:25], v[26:27], v[6:7] op_sel_hi:[1,0]
	v_pk_mul_f32 v[6:7], v[8:9], v[28:29]
	v_pk_mul_f32 v[8:9], v[10:11], v[30:31]
	v_pk_mul_f32 v[10:11], v[12:13], v[40:41]
	v_pk_mul_f32 v[12:13], v[24:25], v[16:17] op_sel:[0,1] op_sel_hi:[1,0]
	ds_bpermute_b32 v28, v33, v6
	ds_bpermute_b32 v29, v33, v7
	ds_bpermute_b32 v26, v33, v8
	ds_bpermute_b32 v27, v33, v9
	ds_bpermute_b32 v24, v33, v10
	ds_bpermute_b32 v25, v33, v11
	ds_bpermute_b32 v17, v33, v12
	ds_bpermute_b32 v16, v33, v13
	v_cmp_gt_u32_e32 vcc, -2, v14
	v_add_u32_e32 v14, s26, v37
	v_cmp_gt_i32_e64 s[4:5], s59, v14
	s_and_b64 s[6:7], s[4:5], vcc
	s_and_saveexec_b64 s[4:5], s[6:7]
	s_cbranch_execz .LBB0_638
	v_lshlrev_b32_e32 v30, 5, v39
	s_mov_b32 s6, 0xffe0
	v_and_or_b32 v30, v30, s6, v35
	v_lshlrev_b32_e32 v30, 2, v30
	s_waitcnt lgkmcnt(1)
	v_cndmask_b32_e64 v17, v17, -v17, s[0:1]
	v_cndmask_b32_e64 v28, v28, -v28, s[0:1]
	v_cndmask_b32_e64 v29, v29, -v29, s[0:1]
	v_cndmask_b32_e64 v26, v26, -v26, s[0:1]
	v_cndmask_b32_e64 v27, v27, -v27, s[0:1]
	v_cndmask_b32_e64 v24, v24, -v24, s[0:1]
	v_cndmask_b32_e64 v25, v25, -v25, s[0:1]
	s_waitcnt vmcnt(3)
	v_mul_f32_e32 v12, v12, v192
	s_waitcnt vmcnt(1)
	v_mul_f32_e32 v30, v17, v216
	s_waitcnt lgkmcnt(0)
	v_cndmask_b32_e64 v17, v16, -v16, s[0:1]
	v_mov_b32_e32 v16, v13
	v_mov_b32_e32 v216, v193
	v_pk_mul_f32 v[16:17], v[16:17], v[216:217]
	s_waitcnt vmcnt(0)
	v_pk_mul_f32 v[28:29], v[28:29], v[218:219]
	v_pk_mul_f32 v[26:27], v[26:27], v[220:221]
	v_pk_mul_f32 v[24:25], v[24:25], v[214:215]
	v_mov_b32_e32 v13, v16
	v_mov_b32_e32 v31, v17
	v_pk_fma_f32 v[6:7], v[6:7], v[210:211], v[28:29]
	v_pk_fma_f32 v[8:9], v[8:9], v[212:213], v[26:27]
	v_pk_fma_f32 v[10:11], v[10:11], v[190:191], v[24:25]
	v_pk_add_f32 v[12:13], v[12:13], v[30:31]
	s_or_b64 exec, exec, s[4:5]
	v_cmp_gt_i32_e32 vcc, s90, v14
	s_and_saveexec_b64 s[4:5], vcc
	s_cbranch_execnz .LBB0_639

; #define GAS __attribute__((address_space(1)))
; DI float bflo(unsigned u) { return __uint_as_float(u << 16); }
; DI float bfhi(unsigned u) { return __uint_as_float(u & 0xffff0000u); }
; DI float shx(float v, int m, int lane) { return __builtin_bit_cast(float, __builtin_amdgcn_ds_bpermute((lane ^ m) << 2, __builtin_bit_cast(int, v))); }
; DI void phase_qknorm(const Ctx& C, bf16_t* Z, const float* qkg  , const float* ropec, const float* ropes) {
;     ...
;             const u32x4 rw = raw[j];
;             float x[8] = {bflo(rw.x), bfhi(rw.x), bflo(rw.y), bfhi(rw.y), bflo(rw.z), bfhi(rw.z), bflo(rw.w), bfhi(rw.w)};
;             float ss = 0.f;
; #pragma unroll
;             for (int i = 0; i < 8; ++i) ss += x[i] * x[i];
;             ss += shx(ss, 1, lane); ss += shx(ss, 2, lane); ss += shx(ss, 4, lane);
;             const float rstd = 1.f / sqrtf(ss * (1.f / 64.f) + EPS);
;             const f32x4 g0 = *(const GAS f32x4*)(qkg + gi * 64 + 8 * t8), g1 = *(const GAS f32x4*)(qkg + gi * 64 + 8 * t8 + 4);
;             x[0] *= rstd * g0.x; x[1] *= rstd * g0.y; x[2] *= rstd * g0.z; x[3] *= rstd * g0.w; x[4] *= rstd * g1.x; x[5] *= rstd * g1.y; x[6] *= rstd * g1.z; x[7] *= rstd * g1.w;
;             float px[8];
; #pragma unroll
;             for (int i = 0; i < 8; ++i) px[i] = shx(x[i], 2, lane);
;             if (rope && row < NLAT) {
;                 const int tok = row & (SEQ - 1), ab = tok * 32 + (t8 & 1) * 8 + (t8 >> 2) * 16;
;                 const f32x4 c0 = *(const GAS f32x4*)(ropec + ab), c1 = *(const GAS f32x4*)(ropec + ab + 4), s0 = *(const GAS f32x4*)(ropes + ab), s1 = *(const GAS f32x4*)(ropes + ab + 4);
;                 const float cc[8] = {c0.x, c0.y, c0.z, c0.w, c1.x, c1.y, c1.z, c1.w}, sn[8] = {s0.x, s0.y, s0.z, s0.w, s1.x, s1.y, s1.z, s1.w};
;                 const float sg = (t8 & 2) ? 1.f : -1.f;
; #pragma unroll
;                 for (int i = 0; i < 8; ++i) x[i] = x[i] * cc[i] + sg * px[i] * sn[i];
;             }
.LBB0_643:
	s_or_b64 exec, exec, s[4:5]
	v_lshlrev_b32_e32 v6, 8, v10
	v_mov_b32_e32 v7, v1
	v_lshl_add_u64 v[12:13], v[18:19], 0, v[6:7]
	global_load_dwordx4 v[6:9], v[12:13], off
	s_waitcnt lgkmcnt(2)
	global_load_dwordx4 v[22:25], v[12:13], off offset:16
	s_waitcnt lgkmcnt(0)
	v_lshlrev_b32_e32 v16, 16, v2
	v_and_b32_e32 v17, 0xffff0000, v2
	v_and_b32_e32 v12, 0xffff0000, v5
	v_lshlrev_b32_e32 v13, 16, v5
	v_lshlrev_b32_e32 v26, 16, v3
	v_and_b32_e32 v27, 0xffff0000, v3
	v_lshlrev_b32_e32 v28, 16, v4
	v_and_b32_e32 v29, 0xffff0000, v4
	v_pk_mul_f32 v[4:5], v[16:17], v[16:17]
	v_pk_mul_f32 v[30:31], v[26:27], v[26:27]
	v_add_f32_e32 v4, v4, v5
	v_add_f32_e32 v4, v30, v4
	v_pk_mul_f32 v[38:39], v[28:29], v[28:29]
	v_add_f32_e32 v4, v31, v4
	v_add_f32_e32 v4, v38, v4
	v_pk_mul_f32 v[2:3], v[12:13], v[12:13]
	v_add_f32_e32 v4, v39, v4
	v_add_f32_e32 v3, v3, v4
	v_add_f32_e32 v2, v2, v3
	ds_bpermute_b32 v3, v32, v2
	s_waitcnt lgkmcnt(0)
	v_add_f32_e32 v2, v2, v3
	ds_bpermute_b32 v3, v33, v2
	s_waitcnt lgkmcnt(0)
	v_add_f32_e32 v2, v2, v3
	ds_bpermute_b32 v3, v34, v2
	s_waitcnt lgkmcnt(0)
	v_add_f32_e32 v2, v2, v3
	v_fmamk_f32 v2, v2, 0x3c800000, v227
	v_mul_f32_e32 v3, 0x4f800000, v2
	v_cmp_gt_f32_e32 vcc, s67, v2
	s_nop 1
	v_cndmask_b32_e32 v2, v2, v3, vcc
	v_sqrt_f32_e32 v3, v2
	s_nop 0
	v_add_u32_e32 v4, -1, v3
	v_add_u32_e32 v5, 1, v3
	v_fma_f32 v11, -v4, v3, v2
	v_fma_f32 v15, -v5, v3, v2
	v_cmp_ge_f32_e64 s[4:5], 0, v11
	v_add_u32_e32 v11, -4, v10
	s_nop 0
	v_cndmask_b32_e64 v3, v3, v4, s[4:5]
	v_cmp_lt_f32_e64 s[4:5], 0, v15
	s_nop 1
	v_cndmask_b32_e64 v3, v3, v5, s[4:5]
	v_mul_f32_e32 v4, 0x37800000, v3
	v_cndmask_b32_e32 v3, v3, v4, vcc
	v_cmp_class_f32_e32 vcc, v2, v228
	s_nop 1
	v_cndmask_b32_e32 v2, v3, v2, vcc
	v_div_scale_f32 v3, s[4:5], v2, v2, 1.0
	v_rcp_f32_e32 v4, v3
	v_div_scale_f32 v5, vcc, 1.0, v2, 1.0
	v_fma_f32 v15, -v3, v4, 1.0
	v_fmac_f32_e32 v4, v15, v4
	v_mul_f32_e32 v15, v5, v4
	v_fma_f32 v30, -v3, v15, v5
	v_fmac_f32_e32 v15, v30, v4
	v_fma_f32 v3, -v3, v15, v5
	v_div_fmas_f32 v3, v3, v4, v15
	v_div_fixup_f32 v2, v3, v2, 1.0
	s_waitcnt vmcnt(1)
	v_pk_mul_f32 v[4:5], v[6:7], v[2:3] op_sel_hi:[1,0]
	v_pk_mul_f32 v[6:7], v[8:9], v[2:3] op_sel_hi:[1,0]
	s_waitcnt vmcnt(0)
	v_pk_mul_f32 v[8:9], v[22:23], v[2:3] op_sel_hi:[1,0]
	v_pk_mul_f32 v[22:23], v[24:25], v[2:3] op_sel_hi:[1,0]
	v_pk_mul_f32 v[2:3], v[4:5], v[16:17]
	v_pk_mul_f32 v[4:5], v[6:7], v[26:27]
	v_pk_mul_f32 v[6:7], v[8:9], v[28:29]
	v_pk_mul_f32 v[8:9], v[22:23], v[12:13] op_sel:[0,1] op_sel_hi:[1,0]
	ds_bpermute_b32 v23, v33, v2
	ds_bpermute_b32 v24, v33, v3
	ds_bpermute_b32 v17, v33, v4
	ds_bpermute_b32 v22, v33, v5
	ds_bpermute_b32 v15, v33, v6
	ds_bpermute_b32 v16, v33, v7
	ds_bpermute_b32 v13, v33, v8
	ds_bpermute_b32 v12, v33, v9
	v_cmp_gt_u32_e32 vcc, -2, v11
	v_add_u32_e32 v11, s26, v14
	v_cmp_gt_i32_e64 s[4:5], s59, v11
	s_and_b64 s[6:7], s[4:5], vcc
	s_and_saveexec_b64 s[4:5], s[6:7]
	s_cbranch_execz .LBB0_645
	v_lshlrev_b32_e32 v14, 5, v36
	s_mov_b32 s6, 0xffe0
	v_and_or_b32 v14, v14, s6, v35
	v_lshlrev_b32_e32 v14, 2, v14
	s_waitcnt lgkmcnt(1)
	v_cndmask_b32_e64 v13, v13, -v13, s[0:1]
	v_cndmask_b32_e64 v30, v23, -v23, s[0:1]
	v_cndmask_b32_e64 v31, v24, -v24, s[0:1]
	v_cndmask_b32_e64 v14, v15, -v15, s[0:1]
	v_cndmask_b32_e64 v15, v16, -v16, s[0:1]
	s_waitcnt vmcnt(3)
	v_mul_f32_e32 v8, v8, v224
	s_waitcnt vmcnt(1)
	v_mul_f32_e32 v16, v13, v246
	s_waitcnt lgkmcnt(0)
	v_cndmask_b32_e64 v13, v12, -v12, s[0:1]
	v_mov_b32_e32 v12, v9
	v_mov_b32_e32 v246, v225
	s_waitcnt vmcnt(0)
	v_pk_mul_f32 v[24:25], v[30:31], v[138:139]
	v_cndmask_b32_e64 v30, v17, -v17, s[0:1]
	v_cndmask_b32_e64 v31, v22, -v22, s[0:1]
	v_pk_mul_f32 v[12:13], v[12:13], v[246:247]
	v_pk_mul_f32 v[22:23], v[30:31], v[140:141]
	v_pk_mul_f32 v[14:15], v[14:15], v[244:245]
	v_mov_b32_e32 v9, v12
	v_mov_b32_e32 v17, v13
	v_pk_fma_f32 v[2:3], v[2:3], v[240:241], v[24:25]
	v_pk_fma_f32 v[4:5], v[4:5], v[242:243], v[22:23]
	v_pk_fma_f32 v[6:7], v[6:7], v[222:223], v[14:15]
	v_pk_add_f32 v[8:9], v[8:9], v[16:17]
